# attention loops: counted lgkmcnt waits per MFMA (each QK/PV MFMA waits only for the LDS fragment reads it consumes) instead of one lgkmcnt(0)
# speedup vs baseline: 1.0081x; 1.0000x over previous
.LBB0_106:
	s_lshl_b64 s[14:15], s[4:5], 17
	s_lshl_b32 s4, s37, 13
	v_lshl_add_u64 v[172:173], v[146:147], 0, s[14:15]
	s_add_i32 s4, s33, s4
	v_lshl_add_u64 v[172:173], v[172:173], 0, s[20:21]
	s_add_i32 m0, s4, 0x9000
	global_load_lds_dwordx4 v[172:173], off
	s_waitcnt lgkmcnt(11)
	v_mfma_f32_32x32x16_bf16 v[48:63], v[48:51], v[82:85], 0
	s_waitcnt lgkmcnt(9)
	v_mfma_f32_32x32x16_bf16 v[64:79], v[64:67], v[82:85], 0
	v_mfma_f32_32x32x16_bf16 v[48:63], v[106:109], v[86:89], v[48:63]
	s_waitcnt lgkmcnt(8)
	v_mfma_f32_32x32x16_bf16 v[64:79], v[110:113], v[86:89], v[64:79]
	s_waitcnt lgkmcnt(7)
	v_mfma_f32_32x32x16_bf16 v[48:63], v[114:117], v[90:93], v[48:63]
	s_waitcnt lgkmcnt(5)
	v_mfma_f32_32x32x16_bf16 v[64:79], v[122:125], v[90:93], v[64:79]
	v_mfma_f32_32x32x16_bf16 v[48:63], v[118:121], v[94:97], v[48:63]
	s_waitcnt lgkmcnt(4)
	v_mfma_f32_32x32x16_bf16 v[64:79], v[126:129], v[94:97], v[64:79]
	s_waitcnt lgkmcnt(3)
	v_mfma_f32_32x32x16_bf16 v[48:63], v[132:135], v[98:101], v[48:63]
	s_waitcnt lgkmcnt(2)
	v_mfma_f32_32x32x16_bf16 v[64:79], v[160:163], v[98:101], v[64:79]
	s_waitcnt lgkmcnt(1)
	v_mfma_f32_32x32x16_bf16 v[48:63], v[164:167], v[102:105], v[48:63]
	s_waitcnt lgkmcnt(0)
	v_mfma_f32_32x32x16_bf16 v[64:79], v[168:171], v[102:105], v[64:79]
	v_lshl_add_u32 v108, s43, 13, v131
	ds_read_b64_tr_b16 v[132:133], v108 offset:0
	ds_read_b64_tr_b16 v[134:135], v108 offset:1024
	ds_read_b64_tr_b16 v[160:161], v108 offset:64
	ds_read_b64_tr_b16 v[162:163], v108 offset:1088
	ds_read_b64_tr_b16 v[126:127], v108 offset:2048
	ds_read_b64_tr_b16 v[128:129], v108 offset:3072
	ds_read_b64_tr_b16 v[122:123], v108 offset:2112
	ds_read_b64_tr_b16 v[124:125], v108 offset:3136
	ds_read_b64_tr_b16 v[118:119], v108 offset:4096
	ds_read_b64_tr_b16 v[120:121], v108 offset:5120
	ds_read_b64_tr_b16 v[114:115], v108 offset:4160
	ds_read_b64_tr_b16 v[116:117], v108 offset:5184
	ds_read_b64_tr_b16 v[110:111], v108 offset:6144
	ds_read_b64_tr_b16 v[112:113], v108 offset:7168
	ds_read_b64_tr_b16 v[106:107], v108 offset:6208
	ds_read_b64_tr_b16 v[108:109], v108 offset:7232
	s_nop 8
	v_exp_f32_e32 v50, v50
	v_exp_f32_e32 v51, v51
	v_exp_f32_e32 v52, v52
	v_exp_f32_e32 v53, v53
	v_exp_f32_e32 v54, v54
	v_exp_f32_e32 v55, v55
	v_exp_f32_e32 v48, v48
	v_exp_f32_e32 v49, v49
	v_add_f32_e32 v32, v32, v50
	v_add_f32_e32 v33, v33, v51
	v_add_f32_e32 v34, v34, v52
	v_add_f32_e32 v35, v35, v53
	v_add_f32_e32 v32, v32, v54
	v_add_f32_e32 v33, v33, v55
	v_add_f32_e32 v34, v34, v48
	v_add_f32_e32 v35, v35, v49
	s_waitcnt lgkmcnt(14)
	v_cvt_pk_bf16_f32 v48, v48, v49
	v_cvt_pk_bf16_f32 v49, v50, v51
	v_cvt_pk_bf16_f32 v50, v52, v53
	v_cvt_pk_bf16_f32 v51, v54, v55
	s_nop 1
	v_mfma_f32_32x32x16_bf16 v[0:15], v[132:135], v[48:51], v[0:15]
	v_exp_f32_e32 v56, v56
	v_exp_f32_e32 v57, v57
	v_exp_f32_e32 v58, v58
	v_exp_f32_e32 v59, v59
	v_exp_f32_e32 v60, v60
	v_exp_f32_e32 v61, v61
	v_exp_f32_e32 v62, v62
	s_waitcnt lgkmcnt(12)
	v_mfma_f32_32x32x16_bf16 v[16:31], v[160:163], v[48:51], v[16:31]
	v_exp_f32_e32 v63, v63
	v_exp_f32_e32 v64, v64
	v_exp_f32_e32 v65, v65
	v_exp_f32_e32 v66, v66
	v_exp_f32_e32 v67, v67
	v_exp_f32_e32 v68, v68
	v_exp_f32_e32 v69, v69
	v_add_f32_e32 v32, v32, v56
	v_add_f32_e32 v33, v33, v57
	v_add_f32_e32 v34, v34, v58
	v_add_f32_e32 v35, v35, v59
	v_add_f32_e32 v32, v32, v60
	v_add_f32_e32 v33, v33, v61
	v_add_f32_e32 v34, v34, v62
	v_add_f32_e32 v35, v35, v63
	v_cvt_pk_bf16_f32 v48, v56, v57
	v_cvt_pk_bf16_f32 v49, v58, v59
	v_cvt_pk_bf16_f32 v50, v60, v61
	v_cvt_pk_bf16_f32 v51, v62, v63
	v_exp_f32_e32 v70, v70
	v_exp_f32_e32 v71, v71
	v_exp_f32_e32 v72, v72
	s_waitcnt lgkmcnt(10)
	v_mfma_f32_32x32x16_bf16 v[0:15], v[126:129], v[48:51], v[0:15]
	v_exp_f32_e32 v73, v73
	v_exp_f32_e32 v74, v74
	v_exp_f32_e32 v75, v75
	v_exp_f32_e32 v76, v76
	v_exp_f32_e32 v77, v77
	v_exp_f32_e32 v78, v78
	v_exp_f32_e32 v79, v79
	s_waitcnt lgkmcnt(8)
	v_mfma_f32_32x32x16_bf16 v[16:31], v[122:125], v[48:51], v[16:31]
	s_mov_b64 s[14:15], -1
	s_and_b64 vcc, exec, s[40:41]
	v_add_f32_e32 v32, v32, v64
	v_add_f32_e32 v33, v33, v65
	v_add_f32_e32 v34, v34, v66
	v_add_f32_e32 v35, v35, v67
	v_add_f32_e32 v32, v32, v68
	v_add_f32_e32 v33, v33, v69
	v_add_f32_e32 v34, v34, v70
	v_add_f32_e32 v35, v35, v71
	v_cvt_pk_bf16_f32 v48, v64, v65
	v_cvt_pk_bf16_f32 v49, v66, v67
	v_cvt_pk_bf16_f32 v50, v68, v69
	v_cvt_pk_bf16_f32 v51, v70, v71
	s_nop 0
	s_waitcnt lgkmcnt(6)
	v_mfma_f32_32x32x16_bf16 v[0:15], v[118:121], v[48:51], v[0:15]
	s_waitcnt lgkmcnt(4)
	v_mfma_f32_32x32x16_bf16 v[16:31], v[114:117], v[48:51], v[16:31]
	v_add_f32_e32 v32, v32, v72
	v_add_f32_e32 v33, v33, v73
	v_add_f32_e32 v34, v34, v74
	v_add_f32_e32 v35, v35, v75
	v_add_f32_e32 v32, v32, v76
	v_add_f32_e32 v33, v33, v77
	v_add_f32_e32 v34, v34, v78
	v_add_f32_e32 v35, v35, v79
	v_cvt_pk_bf16_f32 v48, v72, v73
	v_cvt_pk_bf16_f32 v49, v74, v75
	v_cvt_pk_bf16_f32 v50, v76, v77
	v_cvt_pk_bf16_f32 v51, v78, v79
	s_nop 0
	s_waitcnt lgkmcnt(2)
	v_mfma_f32_32x32x16_bf16 v[0:15], v[110:113], v[48:51], v[0:15]
	s_waitcnt lgkmcnt(0)
	v_mfma_f32_32x32x16_bf16 v[16:31], v[106:109], v[48:51], v[16:31]
	s_cbranch_vccz .LBB0_108
	s_waitcnt vmcnt(2)
	s_mov_b64 s[14:15], 0

.LBB0_117:
	s_lshl_b64 s[14:15], s[4:5], 17
	s_lshl_b32 s4, s43, 13
	v_lshl_add_u64 v[48:49], v[146:147], 0, s[14:15]
	s_add_i32 s4, s33, s4
	v_lshl_add_u64 v[48:49], v[48:49], 0, s[20:21]
	s_add_i32 m0, s4, 0x9000
	s_sub_i32 s4, s49, 63
	global_load_lds_dwordx4 v[48:49], off
	s_cmp_gt_i32 s4, s48
	s_cbranch_scc1 .LBB0_125
	s_mul_i32 s4, s52, 0x3000
	s_add_i32 s4, s4, 16
	v_add_u32_e32 v52, s4, v149
	ds_read_b128 v[48:51], v52
	ds_read_b128 v[106:109], v52 offset:32
	ds_read_b128 v[64:67], v52 offset:6144
	ds_read_b128 v[110:113], v52 offset:6176
	ds_read_b128 v[114:117], v52 offset:64
	ds_read_b128 v[118:121], v52 offset:96
	ds_read_b128 v[122:125], v52 offset:6208
	ds_read_b128 v[126:129], v52 offset:6240
	v_add_u32_e32 v52, s4, v150
	ds_read_b128 v[130:133], v52
	ds_read_b128 v[134:137], v52 offset:6144
	v_add_u32_e32 v52, s4, v151
	ds_read_b128 v[162:165], v52
	ds_read_b128 v[166:169], v52 offset:6144
	s_waitcnt lgkmcnt(11)
	v_mfma_f32_32x32x16_bf16 v[48:63], v[48:51], v[82:85], 0
	s_waitcnt lgkmcnt(9)
	v_mfma_f32_32x32x16_bf16 v[64:79], v[64:67], v[82:85], 0
	v_mfma_f32_32x32x16_bf16 v[48:63], v[106:109], v[86:89], v[48:63]
	s_waitcnt lgkmcnt(8)
	v_mfma_f32_32x32x16_bf16 v[64:79], v[110:113], v[86:89], v[64:79]
	s_waitcnt lgkmcnt(7)
	v_mfma_f32_32x32x16_bf16 v[48:63], v[114:117], v[90:93], v[48:63]
	s_waitcnt lgkmcnt(5)
	v_mfma_f32_32x32x16_bf16 v[64:79], v[122:125], v[90:93], v[64:79]
	v_mfma_f32_32x32x16_bf16 v[48:63], v[118:121], v[94:97], v[48:63]
	s_waitcnt lgkmcnt(4)
	v_mfma_f32_32x32x16_bf16 v[64:79], v[126:129], v[94:97], v[64:79]
	s_waitcnt lgkmcnt(3)
	v_mfma_f32_32x32x16_bf16 v[48:63], v[130:133], v[98:101], v[48:63]
	s_waitcnt lgkmcnt(2)
	v_mfma_f32_32x32x16_bf16 v[64:79], v[134:137], v[98:101], v[64:79]
	s_waitcnt lgkmcnt(1)
	v_mfma_f32_32x32x16_bf16 v[48:63], v[162:165], v[102:105], v[48:63]
	s_waitcnt lgkmcnt(0)
	v_mfma_f32_32x32x16_bf16 v[64:79], v[166:169], v[102:105], v[64:79]
	v_lshl_add_u32 v108, s52, 13, v160
	ds_read_b64_tr_b16 v[134:135], v108 offset:0
	ds_read_b64_tr_b16 v[136:137], v108 offset:1024
	ds_read_b64_tr_b16 v[130:131], v108 offset:64
	ds_read_b64_tr_b16 v[132:133], v108 offset:1088
	ds_read_b64_tr_b16 v[126:127], v108 offset:2048
	ds_read_b64_tr_b16 v[128:129], v108 offset:3072
	ds_read_b64_tr_b16 v[122:123], v108 offset:2112
	ds_read_b64_tr_b16 v[124:125], v108 offset:3136
	ds_read_b64_tr_b16 v[118:119], v108 offset:4096
	ds_read_b64_tr_b16 v[120:121], v108 offset:5120
	ds_read_b64_tr_b16 v[114:115], v108 offset:4160
	ds_read_b64_tr_b16 v[116:117], v108 offset:5184
	ds_read_b64_tr_b16 v[110:111], v108 offset:6144
	ds_read_b64_tr_b16 v[112:113], v108 offset:7168
	ds_read_b64_tr_b16 v[106:107], v108 offset:6208
	ds_read_b64_tr_b16 v[108:109], v108 offset:7232
	s_cmp_le_i32 s49, s34
	s_cbranch_scc1 .LBB0_120
	v_add_u32_e32 v161, s49, v148
	v_subrev_u32_e32 v163, 31, v161
	v_subrev_u32_e32 v162, 63, v161
	v_cmp_le_i32_e32 vcc, v163, v142
	s_nop 3
	v_cndmask_b32_e32 v64, v198, v64, vcc
	v_cmp_lt_i32_e32 vcc, v162, v142
	s_nop 1
	v_cndmask_b32_e32 v49, v198, v49, vcc
	v_cmp_le_i32_e32 vcc, v162, v142
	v_subrev_u32_e32 v162, 30, v161
	s_nop 0
	v_cndmask_b32_e32 v48, v198, v48, vcc
	v_cmp_le_i32_e32 vcc, v162, v142
	v_subrev_u32_e32 v162, 61, v161
	s_nop 0
	v_cndmask_b32_e32 v65, v198, v65, vcc
	v_cmp_le_i32_e32 vcc, v162, v142
	v_subrev_u32_e32 v162, 29, v161
	s_nop 0
	v_cndmask_b32_e32 v50, v198, v50, vcc
	v_cmp_le_i32_e32 vcc, v162, v142
	v_subrev_u32_e32 v162, 60, v161
	s_nop 0
	v_cndmask_b32_e32 v66, v198, v66, vcc
	v_cmp_le_i32_e32 vcc, v162, v142
	v_subrev_u32_e32 v162, 28, v161
	s_nop 0
	v_cndmask_b32_e32 v51, v198, v51, vcc
	v_cmp_le_i32_e32 vcc, v162, v142
	v_subrev_u32_e32 v162, 55, v161
	s_nop 0
	v_cndmask_b32_e32 v67, v198, v67, vcc
	v_cmp_le_i32_e32 vcc, v162, v142
	v_subrev_u32_e32 v162, 23, v161
	s_nop 0
	v_cndmask_b32_e32 v52, v198, v52, vcc
	v_cmp_le_i32_e32 vcc, v162, v142
	v_subrev_u32_e32 v162, 54, v161
	s_nop 0
	v_cndmask_b32_e32 v68, v198, v68, vcc
	v_cmp_le_i32_e32 vcc, v162, v142
	v_subrev_u32_e32 v162, 22, v161
	s_nop 0
	v_cndmask_b32_e32 v53, v198, v53, vcc
	v_cmp_le_i32_e32 vcc, v162, v142
	v_subrev_u32_e32 v162, 53, v161
	s_nop 0
	v_cndmask_b32_e32 v69, v198, v69, vcc
	v_cmp_le_i32_e32 vcc, v162, v142
	v_subrev_u32_e32 v162, 21, v161
	s_nop 0
	v_cndmask_b32_e32 v54, v198, v54, vcc
	v_cmp_le_i32_e32 vcc, v162, v142
	v_subrev_u32_e32 v162, 52, v161
	s_nop 0
	v_cndmask_b32_e32 v70, v198, v70, vcc
	v_cmp_le_i32_e32 vcc, v162, v142
	v_subrev_u32_e32 v162, 20, v161
	s_nop 0
	v_cndmask_b32_e32 v55, v198, v55, vcc
	v_cmp_le_i32_e32 vcc, v162, v142
	v_subrev_u32_e32 v162, 47, v161
	s_nop 0
	v_cndmask_b32_e32 v71, v198, v71, vcc
	v_cmp_le_i32_e32 vcc, v162, v142
	v_add_u32_e32 v162, -15, v161
	s_nop 0
	v_cndmask_b32_e32 v56, v198, v56, vcc
	v_cmp_le_i32_e32 vcc, v162, v142
	v_subrev_u32_e32 v162, 46, v161
	s_nop 0
	v_cndmask_b32_e32 v72, v198, v72, vcc
	v_cmp_le_i32_e32 vcc, v162, v142
	v_add_u32_e32 v162, -14, v161
	s_nop 0
	v_cndmask_b32_e32 v57, v198, v57, vcc
	v_cmp_le_i32_e32 vcc, v162, v142
	v_subrev_u32_e32 v162, 45, v161
	s_nop 0
	v_cndmask_b32_e32 v73, v198, v73, vcc
	v_cmp_le_i32_e32 vcc, v162, v142
	v_add_u32_e32 v162, -13, v161
	s_nop 0
	v_cndmask_b32_e32 v58, v198, v58, vcc
	v_cmp_le_i32_e32 vcc, v162, v142
	v_subrev_u32_e32 v162, 44, v161
	s_nop 0
	v_cndmask_b32_e32 v74, v198, v74, vcc
	v_cmp_le_i32_e32 vcc, v162, v142
	v_add_u32_e32 v162, -12, v161
	s_nop 0
	v_cndmask_b32_e32 v59, v198, v59, vcc
	v_cmp_le_i32_e32 vcc, v162, v142
	v_subrev_u32_e32 v162, 39, v161
	s_nop 0
	v_cndmask_b32_e32 v75, v198, v75, vcc
	v_cmp_le_i32_e32 vcc, v162, v142
	v_add_u32_e32 v162, -7, v161
	s_nop 0
	v_cndmask_b32_e32 v60, v198, v60, vcc
	v_cmp_le_i32_e32 vcc, v162, v142
	v_subrev_u32_e32 v162, 38, v161
	s_nop 0
	v_cndmask_b32_e32 v76, v198, v76, vcc
	v_cmp_le_i32_e32 vcc, v162, v142
	v_add_u32_e32 v162, -6, v161
	s_nop 0
	v_cndmask_b32_e32 v61, v198, v61, vcc
	v_cmp_le_i32_e32 vcc, v162, v142
	v_subrev_u32_e32 v162, 37, v161
	s_nop 0
	v_cndmask_b32_e32 v77, v198, v77, vcc
	v_cmp_le_i32_e32 vcc, v162, v142
	v_add_u32_e32 v162, -5, v161
	s_nop 0
	v_cndmask_b32_e32 v62, v198, v62, vcc
	v_cmp_le_i32_e32 vcc, v162, v142
	v_subrev_u32_e32 v162, 36, v161
	v_add_u32_e32 v161, -4, v161
	v_cndmask_b32_e32 v78, v198, v78, vcc
	v_cmp_le_i32_e32 vcc, v162, v142
	s_nop 1
	v_cndmask_b32_e32 v63, v198, v63, vcc
	v_cmp_le_i32_e32 vcc, v161, v142
	s_nop 1
	v_cndmask_b32_e32 v79, v198, v79, vcc
